# residual GEMM epilogue: second-half residual loads hoisted beside the first half's
# baseline (speedup 1.0000x reference)
; __device__ __forceinline__ unsigned cvt_pk_bf16(float lo, float hi) { unsigned r; asm volatile("v_cvt_pk_bf16_f32 %0, %1, %2" : "=v"(r) : "v"(lo), "v"(hi)); return r; }
;     __device__ __forceinline__ void operator()(const f32x4 (&acc)[2][2][4][2], const Unit& u, int wr, int wc, int fr, int fq) const {
;         const int row0 = u.pm * BM + wr * 64 + fr, col0 = u.pn * BM + wc * 32 + 8 * fq;
;         const float alpha = (u.pass & 1) ? -this->alpha : this->alpha;
; #pragma unroll
;         for (int ai = 0; ai < 2; ++ai) {
;             u32x4 bb[4][2];
; #pragma unroll
;             for (int m = 0; m < 4; ++m)
; #pragma unroll
;                 for (int bj = 0; bj < 2; ++bj) bb[m][bj] = *(const u32x4*)(xb + (size_t)(row0 + ai * HALF + m * 16) * DM + col0 + bj * HALF);
;             asm volatile("" ::: "memory");
; #pragma unroll
;             for (int m = 0; m < 4; ++m) {
;                 const int row = row0 + ai * HALF + m * 16;
;                 bf16_t* xp = xb + (size_t)row * DM + col0;
;                 float ssq = 0.f;
; #pragma unroll
;                 for (int bj = 0; bj < 2; ++bj) {
;                     const u32x4 b = bb[m][bj];
;                     float v[8];
; #pragma unroll
;                     for (int j = 0; j < 4; ++j) {
;                         v[2 * j] = __uint_as_float(b[j] << 16) + acc[ai][bj][m][j >> 1][(2 * j) & 3] * alpha;
;                         v[2 * j + 1] = __uint_as_float(b[j] & 0xffff0000u) + acc[ai][bj][m][j >> 1][(2 * j + 1) & 3] * alpha;
;                     }
;                     u32x4 w; w.x = cvt_pk_bf16(v[0], v[1]); w.y = cvt_pk_bf16(v[2], v[3]); w.z = cvt_pk_bf16(v[4], v[5]); w.w = cvt_pk_bf16(v[6], v[7]);
;                     *(u32x4*)(xp + bj * HALF) = w;
; #pragma unroll
;                     for (int j = 0; j < 4; ++j) { const float r0 = __uint_as_float(w[j] << 16), r1 = __uint_as_float(w[j] & 0xffff0000u); ssq += r0 * r0 + r1 * r1; }
;                 }
;                 ssq = fq_sum(ssq);
;                 if (fq == 0) SS[(size_t)row * 16 + u.pn * 4 + wc] = ssq;
;             }
.LBB0_621:
	v_lshl_or_b32 v176, s15, 8, v206
	v_lshl_add_u32 v180, s84, 8, v157
	v_ashrrev_i32_e32 v177, 31, v176
	v_lshlrev_b64 v[130:131], 1, v[176:177]
	v_ashrrev_i32_e32 v181, 31, v180
	v_lshl_add_u64 v[178:179], s[18:19], 0, v[130:131]
	v_lshlrev_b64 v[132:133], 11, v[180:181]
	v_lshl_add_u64 v[134:135], v[178:179], 0, v[132:133]
	global_load_dwordx4 v[210:213], v[134:135], off
	global_load_dwordx4 v[214:217], v[134:135], off offset:256
	v_add_co_u32_e32 v226, vcc, 0x40000, v134
	s_nop 1
	v_addc_co_u32_e32 v227, vcc, 0, v135, vcc
	global_load_dwordx4 v[230:233], v[226:227], off offset:256
	global_load_dwordx4 v[226:229], v[226:227], off
	v_or_b32_e32 v188, 16, v180
	v_or_b32_e32 v184, 32, v180
	s_bitcmp0_b32 s28, 0
	v_or_b32_e32 v182, 48, v180
	v_ashrrev_i32_e32 v189, 31, v188
	v_ashrrev_i32_e32 v185, 31, v184
	v_mov_b32_e32 v134, s44
	s_cselect_b64 s[38:39], -1, 0
	v_ashrrev_i32_e32 v183, 31, v182
	v_lshlrev_b64 v[192:193], 11, v[188:189]
	v_lshlrev_b64 v[190:191], 11, v[184:185]
	v_cndmask_b32_e64 v208, -v134, v134, s[38:39]
	v_lshlrev_b64 v[186:187], 11, v[182:183]
	v_lshl_add_u64 v[132:133], s[18:19], 0, v[132:133]
	v_lshl_add_u64 v[134:135], v[178:179], 0, v[192:193]
	v_lshl_add_u64 v[136:137], v[178:179], 0, v[190:191]
	v_lshl_add_u64 v[194:195], v[178:179], 0, v[186:187]
	v_lshl_add_u64 v[218:219], v[132:133], 0, v[130:131]
	global_load_dwordx4 v[150:153], v[134:135], off
	global_load_dwordx4 v[146:149], v[134:135], off offset:256
	v_add_co_u32_e32 v234, vcc, 0x40000, v134
	s_nop 1
	v_addc_co_u32_e32 v235, vcc, 0, v135, vcc
	global_load_dwordx4 v[238:241], v[234:235], off offset:256
	global_load_dwordx4 v[234:237], v[234:235], off
	global_load_dwordx4 v[142:145], v[136:137], off
	global_load_dwordx4 v[138:141], v[136:137], off offset:256
	v_add_co_u32_e32 v242, vcc, 0x40000, v136
	s_nop 1
	v_addc_co_u32_e32 v243, vcc, 0, v137, vcc
	global_load_dwordx4 v[246:249], v[242:243], off offset:256
	global_load_dwordx4 v[242:245], v[242:243], off
	s_nop 0
	global_load_dwordx4 v[134:137], v[194:195], off
	global_load_dwordx4 v[130:133], v[194:195], off offset:256
	v_add_co_u32_e32 v250, vcc, 0x40000, v194
	s_nop 1
	v_addc_co_u32_e32 v251, vcc, 0, v195, vcc
	global_load_dwordx4 v[250:253], v[250:251], off
	s_waitcnt vmcnt(0)
	v_lshlrev_b32_e32 v194, 16, v210
	v_and_b32_e32 v195, 0xffff0000, v210
	v_lshlrev_b32_e32 v209, 16, v211
	v_and_b32_e32 v210, 0xffff0000, v211
	v_lshlrev_b32_e32 v221, 16, v214
	v_and_b32_e32 v214, 0xffff0000, v214
	v_lshlrev_b32_e32 v222, 16, v215
	v_and_b32_e32 v215, 0xffff0000, v215
	v_lshlrev_b32_e32 v223, 16, v216
	v_and_b32_e32 v216, 0xffff0000, v216
	v_lshlrev_b32_e32 v211, 16, v212
	v_and_b32_e32 v212, 0xffff0000, v212
	v_lshlrev_b32_e32 v220, 16, v213
	v_and_b32_e32 v213, 0xffff0000, v213
	v_lshlrev_b32_e32 v224, 16, v217
	v_and_b32_e32 v217, 0xffff0000, v217
	v_fmac_f32_e32 v194, v208, v126
	v_fmac_f32_e32 v195, v208, v127
	v_fmac_f32_e32 v209, v208, v128
	v_fmac_f32_e32 v210, v208, v129
	v_fmac_f32_e32 v214, v208, v119
	v_fmac_f32_e32 v215, v208, v121
	v_fmac_f32_e32 v223, v208, v114
	v_fmac_f32_e32 v216, v208, v115
	v_cvt_pk_bf16_f32 v114, v194, v195
	v_cvt_pk_bf16_f32 v115, v209, v210
	v_fmac_f32_e32 v211, v208, v122
	v_and_b32_e32 v119, 0xffff0000, v114
	v_and_b32_e32 v121, 0xffff0000, v115
	v_fmac_f32_e32 v212, v208, v123
	v_fmac_f32_e32 v220, v208, v124
	v_fmac_f32_e32 v213, v208, v125
	v_fmac_f32_e32 v221, v208, v118
	v_fmac_f32_e32 v222, v208, v120
	v_fmac_f32_e32 v224, v208, v116
	v_fmac_f32_e32 v217, v208, v117
	v_cvt_pk_bf16_f32 v116, v211, v212
	v_cvt_pk_bf16_f32 v117, v220, v213
	v_lshlrev_b32_e32 v118, 16, v114
	v_lshlrev_b32_e32 v120, 16, v115
	v_and_b32_e32 v123, 0xffff0000, v116
	v_mul_f32_e32 v119, v119, v119
	v_mul_f32_e32 v121, v121, v121
	global_store_dwordx4 v[218:219], v[114:117], off
	v_lshlrev_b32_e32 v122, 16, v116
	v_lshlrev_b32_e32 v124, 16, v117
	v_and_b32_e32 v117, 0xffff0000, v117
	v_mul_f32_e32 v123, v123, v123
	v_fmac_f32_e32 v119, v118, v118
	v_fmac_f32_e32 v121, v120, v120
	v_mul_f32_e32 v117, v117, v117
	v_fmac_f32_e32 v123, v122, v122
	v_add_f32_e32 v118, v119, v121
	v_cvt_pk_bf16_f32 v114, v221, v214
	v_fmac_f32_e32 v117, v124, v124
	v_add_f32_e32 v118, v118, v123
	v_cvt_pk_bf16_f32 v115, v222, v215
	v_cvt_pk_bf16_f32 v116, v223, v216
	v_add_f32_e32 v118, v118, v117
	v_cvt_pk_bf16_f32 v117, v224, v217
	global_store_dwordx4 v[218:219], v[114:117], off offset:256
	v_lshlrev_b32_e32 v119, 16, v114
	s_nop 0
	v_and_b32_e32 v114, 0xffff0000, v114
	v_mul_f32_e32 v114, v114, v114
	v_fmac_f32_e32 v114, v119, v119
	v_add_f32_e32 v114, v118, v114
	v_lshlrev_b32_e32 v118, 16, v115
	v_and_b32_e32 v115, 0xffff0000, v115
	v_mul_f32_e32 v115, v115, v115
	v_fmac_f32_e32 v115, v118, v118
	v_add_f32_e32 v114, v114, v115
	v_lshlrev_b32_e32 v115, 16, v116
	v_and_b32_e32 v116, 0xffff0000, v116
	v_mul_f32_e32 v116, v116, v116
	v_fmac_f32_e32 v116, v115, v115
	v_add_f32_e32 v114, v114, v116
	v_and_b32_e32 v116, 0xffff0000, v117
	v_lshlrev_b32_e32 v115, 16, v117
	v_mul_f32_e32 v116, v116, v116
	v_fmac_f32_e32 v116, v115, v115
	v_add_f32_e32 v114, v114, v116
	v_mov_b32_e32 v115, v114
	s_nop 1
	v_permlane16_swap_b32_e32 v114, v115
	v_add_f32_e32 v114, v114, v115
	v_mov_b32_e32 v115, v114
	s_nop 1
	v_permlane32_swap_b32_e32 v114, v115
	s_and_saveexec_b64 s[68:69], s[6:7]
	s_cbranch_execz .LBB0_623
	v_add_f32_e32 v116, v114, v115
	s_lshl_b32 s38, s15, 2
	v_lshlrev_b64 v[114:115], 6, v[180:181]
	s_ashr_i32 s39, s38, 31
	v_lshl_add_u64 v[114:115], s[20:21], 0, v[114:115]
	v_lshl_add_u64 v[114:115], s[38:39], 2, v[114:115]
	s_lshl_b32 s28, s77, 2
	v_lshl_add_u64 v[114:115], v[114:115], 0, s[28:29]
	global_store_dword v[114:115], v116, off

; __device__ __forceinline__ unsigned cvt_pk_bf16(float lo, float hi) { unsigned r; asm volatile("v_cvt_pk_bf16_f32 %0, %1, %2" : "=v"(r) : "v"(lo), "v"(hi)); return r; }
;     __device__ __forceinline__ void operator()(const f32x4 (&acc)[2][2][4][2], const Unit& u, int wr, int wc, int fr, int fq) const {
;     ...
;                 for (int bj = 0; bj < 2; ++bj) bb[m][bj] = *(const u32x4*)(xb + (size_t)(row0 + ai * HALF + m * 16) * DM + col0 + bj * HALF);
;             asm volatile("" ::: "memory");
; #pragma unroll
;             for (int m = 0; m < 4; ++m) {
;                 const int row = row0 + ai * HALF + m * 16;
;                 bf16_t* xp = xb + (size_t)row * DM + col0;
;                 float ssq = 0.f;
; #pragma unroll
;                 for (int bj = 0; bj < 2; ++bj) {
;                     const u32x4 b = bb[m][bj];
;                     float v[8];
; #pragma unroll
;                     for (int j = 0; j < 4; ++j) {
;                         v[2 * j] = __uint_as_float(b[j] << 16) + acc[ai][bj][m][j >> 1][(2 * j) & 3] * alpha;
;                         v[2 * j + 1] = __uint_as_float(b[j] & 0xffff0000u) + acc[ai][bj][m][j >> 1][(2 * j + 1) & 3] * alpha;
;                     }
;                     u32x4 w; w.x = cvt_pk_bf16(v[0], v[1]); w.y = cvt_pk_bf16(v[2], v[3]); w.z = cvt_pk_bf16(v[4], v[5]); w.w = cvt_pk_bf16(v[6], v[7]);
;                     *(u32x4*)(xp + bj * HALF) = w;
; #pragma unroll
;                     for (int j = 0; j < 4; ++j) { const float r0 = __uint_as_float(w[j] << 16), r1 = __uint_as_float(w[j] & 0xffff0000u); ssq += r0 * r0 + r1 * r1; }
;                 }
;                 ssq = fq_sum(ssq);
;                 if (fq == 0) SS[(size_t)row * 16 + u.pn * 4 + wc] = ssq;
.LBB0_629:
	s_or_b64 exec, exec, s[68:69]
	v_add_u32_e32 v106, 0x80, v180
	v_ashrrev_i32_e32 v107, 31, v106
	v_lshlrev_b64 v[108:109], 11, v[106:107]
	v_lshl_add_u64 v[66:67], v[178:179], 0, v[108:109]
	v_add_u32_e32 v100, 0x90, v180
	v_ashrrev_i32_e32 v101, 31, v100
	v_add_u32_e32 v96, 0xa0, v180
	v_lshlrev_b64 v[104:105], 11, v[100:101]
	v_ashrrev_i32_e32 v97, 31, v96
	v_add_u32_e32 v94, 0xb0, v180
	v_lshl_add_u64 v[66:67], v[178:179], 0, v[104:105]
	v_lshlrev_b64 v[102:103], 11, v[96:97]
	v_ashrrev_i32_e32 v95, 31, v94
	v_lshl_add_u64 v[66:67], v[178:179], 0, v[102:103]
	v_lshlrev_b64 v[98:99], 11, v[94:95]
	v_lshl_add_u64 v[66:67], v[178:179], 0, v[98:99]
	s_nop 0
	global_load_dwordx4 v[66:69], v[66:67], off offset:256
	v_lshl_add_u64 v[108:109], s[18:19], 0, v[108:109]
	v_lshl_add_u64 v[108:109], v[176:177], 1, v[108:109]
	s_waitcnt vmcnt(7)
	v_lshlrev_b32_e32 v114, 16, v226
	v_fmac_f32_e32 v114, v208, v62
	v_and_b32_e32 v62, 0xffff0000, v226
	v_fmac_f32_e32 v62, v208, v63
	v_lshlrev_b32_e32 v63, 16, v227
	v_fmac_f32_e32 v63, v208, v64
	v_and_b32_e32 v64, 0xffff0000, v227
	v_fmac_f32_e32 v64, v208, v65
	v_lshlrev_b32_e32 v65, 16, v228
	v_fmac_f32_e32 v65, v208, v58
	v_and_b32_e32 v226, 0xffff0000, v228
	v_lshlrev_b32_e32 v227, 16, v229
	v_and_b32_e32 v228, 0xffff0000, v229
	v_cvt_pk_bf16_f32 v58, v114, v62
	v_fmac_f32_e32 v226, v208, v59
	v_fmac_f32_e32 v227, v208, v60
	v_fmac_f32_e32 v228, v208, v61
	v_cvt_pk_bf16_f32 v59, v63, v64
	v_cvt_pk_bf16_f32 v60, v65, v226
	v_cvt_pk_bf16_f32 v61, v227, v228
	global_store_dwordx4 v[108:109], v[58:61], off
	v_lshlrev_b32_e32 v62, 16, v58
	s_nop 0
	v_and_b32_e32 v58, 0xffff0000, v58
	v_mul_f32_e32 v58, v58, v58
	v_fmac_f32_e32 v58, v62, v62
	v_lshlrev_b32_e32 v62, 16, v59
	v_and_b32_e32 v59, 0xffff0000, v59
	v_mul_f32_e32 v59, v59, v59
	v_fmac_f32_e32 v59, v62, v62
	v_add_f32_e32 v58, v58, v59
	v_lshlrev_b32_e32 v59, 16, v60
	v_and_b32_e32 v60, 0xffff0000, v60
	v_mul_f32_e32 v60, v60, v60
	v_fmac_f32_e32 v60, v59, v59
	v_add_f32_e32 v58, v58, v60
	v_and_b32_e32 v60, 0xffff0000, v61
	v_lshlrev_b32_e32 v59, 16, v61
	v_mul_f32_e32 v60, v60, v60
	v_fmac_f32_e32 v60, v59, v59
	s_waitcnt vmcnt(7)
	v_lshlrev_b32_e32 v59, 16, v230
	v_fmac_f32_e32 v59, v208, v54
	v_and_b32_e32 v54, 0xffff0000, v230
	v_fmac_f32_e32 v54, v208, v55
	v_lshlrev_b32_e32 v55, 16, v231
	v_fmac_f32_e32 v55, v208, v56
	v_and_b32_e32 v56, 0xffff0000, v231
	v_fmac_f32_e32 v56, v208, v57
	v_lshlrev_b32_e32 v57, 16, v232
	v_add_f32_e32 v58, v58, v60
	v_fmac_f32_e32 v57, v208, v50
	v_and_b32_e32 v60, 0xffff0000, v232
	v_lshlrev_b32_e32 v61, 16, v233
	v_and_b32_e32 v62, 0xffff0000, v233
	v_cvt_pk_bf16_f32 v50, v59, v54
	v_fmac_f32_e32 v60, v208, v51
	v_fmac_f32_e32 v61, v208, v52
	v_fmac_f32_e32 v62, v208, v53
	v_cvt_pk_bf16_f32 v51, v55, v56
	v_cvt_pk_bf16_f32 v52, v57, v60
	v_cvt_pk_bf16_f32 v53, v61, v62
	global_store_dwordx4 v[108:109], v[50:53], off offset:256
	v_lshlrev_b32_e32 v54, 16, v50
	s_nop 0
	v_and_b32_e32 v50, 0xffff0000, v50
	v_mul_f32_e32 v50, v50, v50
	v_fmac_f32_e32 v50, v54, v54
	v_lshlrev_b32_e32 v54, 16, v51
	v_and_b32_e32 v51, 0xffff0000, v51
	v_mul_f32_e32 v51, v51, v51
	v_add_f32_e32 v50, v58, v50
	v_fmac_f32_e32 v51, v54, v54
	v_add_f32_e32 v50, v50, v51
	v_lshlrev_b32_e32 v51, 16, v52
	v_and_b32_e32 v52, 0xffff0000, v52
	v_mul_f32_e32 v52, v52, v52
	v_fmac_f32_e32 v52, v51, v51
	v_add_f32_e32 v50, v50, v52
	v_and_b32_e32 v52, 0xffff0000, v53
	v_lshlrev_b32_e32 v51, 16, v53
	v_mul_f32_e32 v52, v52, v52
	v_fmac_f32_e32 v52, v51, v51
	v_add_f32_e32 v50, v50, v52
	v_mov_b32_e32 v51, v50
	s_nop 1
	v_permlane16_swap_b32_e32 v50, v51
	v_add_f32_e32 v50, v50, v51
	v_mov_b32_e32 v51, v50
	s_nop 1
	v_permlane32_swap_b32_e32 v50, v51
	s_and_saveexec_b64 s[68:69], s[6:7]
	s_cbranch_execz .LBB0_631
	v_add_f32_e32 v52, v50, v51
	s_lshl_b32 s38, s15, 2
	v_lshlrev_b64 v[50:51], 6, v[106:107]
	s_ashr_i32 s39, s38, 31
	v_lshl_add_u64 v[50:51], s[20:21], 0, v[50:51]
	v_lshl_add_u64 v[50:51], s[38:39], 2, v[50:51]
	s_lshl_b32 s28, s77, 2
	v_lshl_add_u64 v[50:51], v[50:51], 0, s[28:29]
	global_store_dword v[50:51], v52, off
.LBB0_631:
	s_or_b64 exec, exec, s[68:69]
	s_waitcnt vmcnt(7)
	v_lshlrev_b32_e32 v52, 16, v234
	v_fmac_f32_e32 v52, v208, v46
	v_and_b32_e32 v46, 0xffff0000, v234
	v_fmac_f32_e32 v46, v208, v47
	v_lshlrev_b32_e32 v47, 16, v235
	v_fmac_f32_e32 v47, v208, v48
	v_and_b32_e32 v48, 0xffff0000, v235
	v_lshl_add_u64 v[50:51], s[18:19], 0, v[104:105]
	v_fmac_f32_e32 v48, v208, v49
	v_lshlrev_b32_e32 v49, 16, v236
	v_lshl_add_u64 v[50:51], v[176:177], 1, v[50:51]
	v_fmac_f32_e32 v49, v208, v42
	v_and_b32_e32 v53, 0xffff0000, v236
	v_lshlrev_b32_e32 v54, 16, v237
	v_and_b32_e32 v55, 0xffff0000, v237
	v_cvt_pk_bf16_f32 v42, v52, v46
	v_fmac_f32_e32 v53, v208, v43
	v_fmac_f32_e32 v54, v208, v44
	v_fmac_f32_e32 v55, v208, v45
	v_cvt_pk_bf16_f32 v43, v47, v48
	v_cvt_pk_bf16_f32 v44, v49, v53
	v_cvt_pk_bf16_f32 v45, v54, v55
	global_store_dwordx4 v[50:51], v[42:45], off
	v_lshlrev_b32_e32 v46, 16, v42
	s_nop 0
	v_and_b32_e32 v42, 0xffff0000, v42
	v_mul_f32_e32 v42, v42, v42
	v_fmac_f32_e32 v42, v46, v46
	v_lshlrev_b32_e32 v46, 16, v43
	v_and_b32_e32 v43, 0xffff0000, v43
	v_mul_f32_e32 v43, v43, v43
	v_fmac_f32_e32 v43, v46, v46
	v_add_f32_e32 v42, v42, v43
	v_lshlrev_b32_e32 v43, 16, v44
	v_and_b32_e32 v44, 0xffff0000, v44
	v_mul_f32_e32 v44, v44, v44
	v_fmac_f32_e32 v44, v43, v43
	v_add_f32_e32 v42, v42, v44
	v_and_b32_e32 v44, 0xffff0000, v45
	v_lshlrev_b32_e32 v43, 16, v45
	v_mul_f32_e32 v44, v44, v44
	v_fmac_f32_e32 v44, v43, v43
	s_waitcnt vmcnt(7)
; __device__ __forceinline__ unsigned cvt_pk_bf16(float lo, float hi) { unsigned r; asm volatile("v_cvt_pk_bf16_f32 %0, %1, %2" : "=v"(r) : "v"(lo), "v"(hi)); return r; }
;     __device__ __forceinline__ void operator()(const f32x4 (&acc)[2][2][4][2], const Unit& u, int wr, int wc, int fr, int fq) const {
;     ...
;                 for (int bj = 0; bj < 2; ++bj) {
;                     const u32x4 b = bb[m][bj];
;                     float v[8];
; #pragma unroll
;                     for (int j = 0; j < 4; ++j) {
;                         v[2 * j] = __uint_as_float(b[j] << 16) + acc[ai][bj][m][j >> 1][(2 * j) & 3] * alpha;
;                         v[2 * j + 1] = __uint_as_float(b[j] & 0xffff0000u) + acc[ai][bj][m][j >> 1][(2 * j + 1) & 3] * alpha;
;                     }
;                     u32x4 w; w.x = cvt_pk_bf16(v[0], v[1]); w.y = cvt_pk_bf16(v[2], v[3]); w.z = cvt_pk_bf16(v[4], v[5]); w.w = cvt_pk_bf16(v[6], v[7]);
;                     *(u32x4*)(xp + bj * HALF) = w;
; #pragma unroll
;                     for (int j = 0; j < 4; ++j) { const float r0 = __uint_as_float(w[j] << 16), r1 = __uint_as_float(w[j] & 0xffff0000u); ssq += r0 * r0 + r1 * r1; }
;                 }
;                 ssq = fq_sum(ssq);
;                 if (fq == 0) SS[(size_t)row * 16 + u.pn * 4 + wc] = ssq;
	v_lshlrev_b32_e32 v43, 16, v238
	v_fmac_f32_e32 v43, v208, v38
	v_and_b32_e32 v38, 0xffff0000, v238
	v_fmac_f32_e32 v38, v208, v39
	v_lshlrev_b32_e32 v39, 16, v239
	v_fmac_f32_e32 v39, v208, v40
	v_and_b32_e32 v40, 0xffff0000, v239
	v_fmac_f32_e32 v40, v208, v41
	v_lshlrev_b32_e32 v41, 16, v240
	v_add_f32_e32 v42, v42, v44
	v_fmac_f32_e32 v41, v208, v34
	v_and_b32_e32 v44, 0xffff0000, v240
	v_lshlrev_b32_e32 v45, 16, v241
	v_and_b32_e32 v46, 0xffff0000, v241
	v_cvt_pk_bf16_f32 v34, v43, v38
	v_fmac_f32_e32 v44, v208, v35
	v_fmac_f32_e32 v45, v208, v36
	v_fmac_f32_e32 v46, v208, v37
	v_cvt_pk_bf16_f32 v35, v39, v40
	v_cvt_pk_bf16_f32 v36, v41, v44
	v_cvt_pk_bf16_f32 v37, v45, v46
	global_store_dwordx4 v[50:51], v[34:37], off offset:256
	v_lshlrev_b32_e32 v38, 16, v34
	s_nop 0
	v_and_b32_e32 v34, 0xffff0000, v34
	v_mul_f32_e32 v34, v34, v34
	v_fmac_f32_e32 v34, v38, v38
	v_lshlrev_b32_e32 v38, 16, v35
	v_and_b32_e32 v35, 0xffff0000, v35
	v_mul_f32_e32 v35, v35, v35
	v_add_f32_e32 v34, v42, v34
	v_fmac_f32_e32 v35, v38, v38
	v_add_f32_e32 v34, v34, v35
	v_lshlrev_b32_e32 v35, 16, v36
	v_and_b32_e32 v36, 0xffff0000, v36
	v_mul_f32_e32 v36, v36, v36
	v_fmac_f32_e32 v36, v35, v35
	v_add_f32_e32 v34, v34, v36
	v_and_b32_e32 v36, 0xffff0000, v37
	v_lshlrev_b32_e32 v35, 16, v37
	v_mul_f32_e32 v36, v36, v36
	v_fmac_f32_e32 v36, v35, v35
	v_add_f32_e32 v34, v34, v36
	v_mov_b32_e32 v35, v34
	s_nop 1
	v_permlane16_swap_b32_e32 v34, v35
	v_add_f32_e32 v34, v34, v35
	v_mov_b32_e32 v35, v34
	s_nop 1
	v_permlane32_swap_b32_e32 v34, v35
	s_and_saveexec_b64 s[68:69], s[6:7]
	s_cbranch_execz .LBB0_633
	v_add_f32_e32 v36, v34, v35
	s_lshl_b32 s38, s15, 2
	v_lshlrev_b64 v[34:35], 6, v[100:101]
	s_ashr_i32 s39, s38, 31
	v_lshl_add_u64 v[34:35], s[20:21], 0, v[34:35]
	v_lshl_add_u64 v[34:35], s[38:39], 2, v[34:35]
	s_lshl_b32 s28, s77, 2
	v_lshl_add_u64 v[34:35], v[34:35], 0, s[28:29]
	global_store_dword v[34:35], v36, off
.LBB0_633:
	s_or_b64 exec, exec, s[68:69]
	s_waitcnt vmcnt(7)
	v_lshlrev_b32_e32 v36, 16, v242
	v_fmac_f32_e32 v36, v208, v30
	v_and_b32_e32 v30, 0xffff0000, v242
	v_fmac_f32_e32 v30, v208, v31
	v_lshlrev_b32_e32 v31, 16, v243
	v_fmac_f32_e32 v31, v208, v32
	v_and_b32_e32 v32, 0xffff0000, v243
	v_lshl_add_u64 v[34:35], s[18:19], 0, v[102:103]
	v_fmac_f32_e32 v32, v208, v33
	v_lshlrev_b32_e32 v33, 16, v244
	v_lshl_add_u64 v[34:35], v[176:177], 1, v[34:35]
	v_fmac_f32_e32 v33, v208, v26
	v_and_b32_e32 v37, 0xffff0000, v244
	v_lshlrev_b32_e32 v38, 16, v245
	v_and_b32_e32 v39, 0xffff0000, v245
	v_cvt_pk_bf16_f32 v26, v36, v30
	v_fmac_f32_e32 v37, v208, v27
	v_fmac_f32_e32 v38, v208, v28
	v_fmac_f32_e32 v39, v208, v29
	v_cvt_pk_bf16_f32 v27, v31, v32
	v_cvt_pk_bf16_f32 v28, v33, v37
	v_cvt_pk_bf16_f32 v29, v38, v39
	global_store_dwordx4 v[34:35], v[26:29], off
	v_lshlrev_b32_e32 v30, 16, v26
	s_nop 0
	v_and_b32_e32 v26, 0xffff0000, v26
	v_mul_f32_e32 v26, v26, v26
	v_fmac_f32_e32 v26, v30, v30
	v_lshlrev_b32_e32 v30, 16, v27
	v_and_b32_e32 v27, 0xffff0000, v27
	v_mul_f32_e32 v27, v27, v27
	v_fmac_f32_e32 v27, v30, v30
	v_add_f32_e32 v26, v26, v27
	v_lshlrev_b32_e32 v27, 16, v28
	v_and_b32_e32 v28, 0xffff0000, v28
	v_mul_f32_e32 v28, v28, v28
	v_fmac_f32_e32 v28, v27, v27
	v_add_f32_e32 v26, v26, v28
	v_and_b32_e32 v28, 0xffff0000, v29
	v_lshlrev_b32_e32 v27, 16, v29
	v_mul_f32_e32 v28, v28, v28
	v_fmac_f32_e32 v28, v27, v27
	s_waitcnt vmcnt(7)
	v_lshlrev_b32_e32 v27, 16, v246
	v_fmac_f32_e32 v27, v208, v22
	v_and_b32_e32 v22, 0xffff0000, v246
	v_fmac_f32_e32 v22, v208, v23
	v_lshlrev_b32_e32 v23, 16, v247
	v_fmac_f32_e32 v23, v208, v24
	v_and_b32_e32 v24, 0xffff0000, v247
	v_fmac_f32_e32 v24, v208, v25
	v_lshlrev_b32_e32 v25, 16, v248
	v_add_f32_e32 v26, v26, v28
	v_fmac_f32_e32 v25, v208, v18
	v_and_b32_e32 v28, 0xffff0000, v248
	v_lshlrev_b32_e32 v29, 16, v249
	v_and_b32_e32 v30, 0xffff0000, v249
	v_cvt_pk_bf16_f32 v18, v27, v22
	v_fmac_f32_e32 v28, v208, v19
	v_fmac_f32_e32 v29, v208, v20
	v_fmac_f32_e32 v30, v208, v21
	v_cvt_pk_bf16_f32 v19, v23, v24
	v_cvt_pk_bf16_f32 v20, v25, v28
	v_cvt_pk_bf16_f32 v21, v29, v30
	global_store_dwordx4 v[34:35], v[18:21], off offset:256
	v_lshlrev_b32_e32 v22, 16, v18
	s_nop 0
	v_and_b32_e32 v18, 0xffff0000, v18
	v_mul_f32_e32 v18, v18, v18
	v_fmac_f32_e32 v18, v22, v22
	v_lshlrev_b32_e32 v22, 16, v19
	v_and_b32_e32 v19, 0xffff0000, v19
	v_mul_f32_e32 v19, v19, v19
	v_add_f32_e32 v18, v26, v18
	v_fmac_f32_e32 v19, v22, v22
	v_add_f32_e32 v18, v18, v19
	v_lshlrev_b32_e32 v19, 16, v20
	v_and_b32_e32 v20, 0xffff0000, v20
	v_mul_f32_e32 v20, v20, v20
	v_fmac_f32_e32 v20, v19, v19
	v_add_f32_e32 v18, v18, v20
	v_and_b32_e32 v20, 0xffff0000, v21
	v_lshlrev_b32_e32 v19, 16, v21
	v_mul_f32_e32 v20, v20, v20
	v_fmac_f32_e32 v20, v19, v19
	v_add_f32_e32 v18, v18, v20
	v_mov_b32_e32 v19, v18
	s_nop 1
	v_permlane16_swap_b32_e32 v18, v19
	v_add_f32_e32 v18, v18, v19
	v_mov_b32_e32 v19, v18
	s_nop 1
	v_permlane32_swap_b32_e32 v18, v19
	s_and_saveexec_b64 s[68:69], s[6:7]
	s_cbranch_execz .LBB0_635
	v_add_f32_e32 v20, v18, v19
	s_lshl_b32 s38, s15, 2
	v_lshlrev_b64 v[18:19], 6, v[96:97]
	s_ashr_i32 s39, s38, 31
	v_lshl_add_u64 v[18:19], s[20:21], 0, v[18:19]
	v_lshl_add_u64 v[18:19], s[38:39], 2, v[18:19]
	s_lshl_b32 s28, s77, 2
	v_lshl_add_u64 v[18:19], v[18:19], 0, s[28:29]
	global_store_dword v[18:19], v20, off
; __device__ __forceinline__ unsigned cvt_pk_bf16(float lo, float hi) { unsigned r; asm volatile("v_cvt_pk_bf16_f32 %0, %1, %2" : "=v"(r) : "v"(lo), "v"(hi)); return r; }
;     __device__ __forceinline__ void operator()(const f32x4 (&acc)[2][2][4][2], const Unit& u, int wr, int wc, int fr, int fq) const {
;     ...
;                 for (int bj = 0; bj < 2; ++bj) {
;                     const u32x4 b = bb[m][bj];
;                     float v[8];
; #pragma unroll
;                     for (int j = 0; j < 4; ++j) {
;                         v[2 * j] = __uint_as_float(b[j] << 16) + acc[ai][bj][m][j >> 1][(2 * j) & 3] * alpha;
;                         v[2 * j + 1] = __uint_as_float(b[j] & 0xffff0000u) + acc[ai][bj][m][j >> 1][(2 * j + 1) & 3] * alpha;
;                     }
;                     u32x4 w; w.x = cvt_pk_bf16(v[0], v[1]); w.y = cvt_pk_bf16(v[2], v[3]); w.z = cvt_pk_bf16(v[4], v[5]); w.w = cvt_pk_bf16(v[6], v[7]);
;                     *(u32x4*)(xp + bj * HALF) = w;
; #pragma unroll
;                     for (int j = 0; j < 4; ++j) { const float r0 = __uint_as_float(w[j] << 16), r1 = __uint_as_float(w[j] & 0xffff0000u); ssq += r0 * r0 + r1 * r1; }
;                 }
;                 ssq = fq_sum(ssq);
;                 if (fq == 0) SS[(size_t)row * 16 + u.pn * 4 + wc] = ssq;
.LBB0_635:
	s_or_b64 exec, exec, s[68:69]
	s_waitcnt vmcnt(7)
	v_lshlrev_b32_e32 v20, 16, v250
	v_fmac_f32_e32 v20, v208, v14
	v_and_b32_e32 v14, 0xffff0000, v250
	v_fmac_f32_e32 v14, v208, v15
	v_lshlrev_b32_e32 v15, 16, v251
	v_fmac_f32_e32 v15, v208, v16
	v_and_b32_e32 v16, 0xffff0000, v251
	v_lshl_add_u64 v[18:19], s[18:19], 0, v[98:99]
	v_fmac_f32_e32 v16, v208, v17
	v_lshlrev_b32_e32 v17, 16, v252
	v_lshl_add_u64 v[18:19], v[176:177], 1, v[18:19]
	v_fmac_f32_e32 v17, v208, v10
	v_and_b32_e32 v21, 0xffff0000, v252
	v_lshlrev_b32_e32 v22, 16, v253
	v_and_b32_e32 v23, 0xffff0000, v253
	v_cvt_pk_bf16_f32 v10, v20, v14
	v_fmac_f32_e32 v21, v208, v11
	v_fmac_f32_e32 v22, v208, v12
	v_fmac_f32_e32 v23, v208, v13
	v_cvt_pk_bf16_f32 v11, v15, v16
	v_cvt_pk_bf16_f32 v12, v17, v21
	v_cvt_pk_bf16_f32 v13, v22, v23
	global_store_dwordx4 v[18:19], v[10:13], off
	v_lshlrev_b32_e32 v14, 16, v10
	s_nop 0
	v_and_b32_e32 v10, 0xffff0000, v10
	v_mul_f32_e32 v10, v10, v10
	v_fmac_f32_e32 v10, v14, v14
	v_lshlrev_b32_e32 v14, 16, v11
	v_and_b32_e32 v11, 0xffff0000, v11
	v_mul_f32_e32 v11, v11, v11
	v_fmac_f32_e32 v11, v14, v14
	v_add_f32_e32 v10, v10, v11
	v_lshlrev_b32_e32 v11, 16, v12
	v_and_b32_e32 v12, 0xffff0000, v12
	v_mul_f32_e32 v12, v12, v12
	v_fmac_f32_e32 v12, v11, v11
	v_add_f32_e32 v10, v10, v12
	v_and_b32_e32 v12, 0xffff0000, v13
	v_lshlrev_b32_e32 v11, 16, v13
	v_mul_f32_e32 v12, v12, v12
	v_fmac_f32_e32 v12, v11, v11
	s_waitcnt vmcnt(7)
	v_lshlrev_b32_e32 v11, 16, v66
	v_fmac_f32_e32 v11, v208, v6
	v_and_b32_e32 v6, 0xffff0000, v66
	v_fmac_f32_e32 v6, v208, v7
	v_lshlrev_b32_e32 v7, 16, v67
	v_fmac_f32_e32 v7, v208, v8
	v_and_b32_e32 v8, 0xffff0000, v67
	v_fmac_f32_e32 v8, v208, v9
	v_lshlrev_b32_e32 v9, 16, v68
	v_add_f32_e32 v10, v10, v12
	v_fmac_f32_e32 v9, v208, v2
	v_and_b32_e32 v12, 0xffff0000, v68
	v_lshlrev_b32_e32 v13, 16, v69
	v_and_b32_e32 v14, 0xffff0000, v69
	v_cvt_pk_bf16_f32 v2, v11, v6
	v_fmac_f32_e32 v12, v208, v3
	v_fmac_f32_e32 v13, v208, v4
	v_fmac_f32_e32 v14, v208, v5
	v_cvt_pk_bf16_f32 v3, v7, v8
	v_cvt_pk_bf16_f32 v4, v9, v12
	v_cvt_pk_bf16_f32 v5, v13, v14
	global_store_dwordx4 v[18:19], v[2:5], off offset:256
	v_lshlrev_b32_e32 v6, 16, v2
	s_nop 0
	v_and_b32_e32 v2, 0xffff0000, v2
	v_mul_f32_e32 v2, v2, v2
	v_fmac_f32_e32 v2, v6, v6
	v_lshlrev_b32_e32 v6, 16, v3
	v_and_b32_e32 v3, 0xffff0000, v3
	v_mul_f32_e32 v3, v3, v3
	v_add_f32_e32 v2, v10, v2
	v_fmac_f32_e32 v3, v6, v6
	v_add_f32_e32 v2, v2, v3
	v_lshlrev_b32_e32 v3, 16, v4
	v_and_b32_e32 v4, 0xffff0000, v4
	v_mul_f32_e32 v4, v4, v4
	v_fmac_f32_e32 v4, v3, v3
	v_add_f32_e32 v2, v2, v4
	v_and_b32_e32 v4, 0xffff0000, v5
	v_lshlrev_b32_e32 v3, 16, v5
	v_mul_f32_e32 v4, v4, v4
	v_fmac_f32_e32 v4, v3, v3
	v_add_f32_e32 v2, v2, v4
	v_mov_b32_e32 v3, v2
	s_nop 1
	v_permlane16_swap_b32_e32 v2, v3
	v_add_f32_e32 v2, v2, v3
	v_mov_b32_e32 v3, v2
	s_nop 1
	v_permlane32_swap_b32_e32 v2, v3
	s_and_saveexec_b64 s[68:69], s[6:7]
	s_cbranch_execz .LBB0_637
	v_add_f32_e32 v4, v2, v3
	s_lshl_b32 s38, s15, 2
	v_lshlrev_b64 v[2:3], 6, v[94:95]
	s_ashr_i32 s39, s38, 31
	v_lshl_add_u64 v[2:3], s[20:21], 0, v[2:3]
	v_lshl_add_u64 v[2:3], s[38:39], 2, v[2:3]
	s_lshl_b32 s28, s77, 2
	v_lshl_add_u64 v[2:3], v[2:3], 0, s[28:29]
	global_store_dword v[2:3], v4, off
